# attention inner loop: V fragments in own registers with their LDS reads issued at the loop top; P.V MFMAs of tile 0 before the exps of tile 1
# baseline (speedup 1.0000x reference)
.LBB0_413:
	v_bitop3_b32 v64, s45, v142, v189 bitop3:0x36
	v_bitop3_b32 v72, s45, v143, v189 bitop3:0x36
	v_bitop3_b32 v80, s44, v142, v189 bitop3:0x36
	v_bitop3_b32 v88, s44, v143, v189 bitop3:0x36
	v_mad_i32_i24 v68, v64, s18, v122
	v_mad_i32_i24 v76, v72, s18, v122
	v_mad_i32_i24 v84, v80, s18, v122
	v_mad_i32_i24 v92, v88, s18, v122
	ds_read_b128 v[64:67], v68 offset:18496
	ds_read_b128 v[68:71], v68 offset:18432
	ds_read_b128 v[72:75], v76 offset:18496
	ds_read_b128 v[76:79], v76 offset:18432
	ds_read_b128 v[80:83], v84 offset:18496
	ds_read_b128 v[84:87], v84 offset:18432
	ds_read_b128 v[88:91], v92 offset:18496
	ds_read_b128 v[92:95], v92 offset:18432
	v_bitop3_b32 v158, s44, v123, v143 bitop3:0xde
	v_bitop3_b32 v159, s44, v130, v143 bitop3:0xde
	v_mad_u32_u24 v186, v158, s18, 0
	v_mad_u32_u24 v187, v159, s18, 0
	v_add_u32_e32 v188, v186, v125
	v_add_u32_e32 v190, v187, v125
	v_add_u32_e32 v186, v186, v131
	v_add_u32_e32 v187, v187, v131
	ds_read_b64_tr_b16 v[226:227], v190 offset:55296
	ds_read_b64_tr_b16 v[230:231], v190 offset:55328
	ds_read_b64_tr_b16 v[224:225], v188 offset:55296
	ds_read_b64_tr_b16 v[228:229], v188 offset:55328
	ds_read_b64_tr_b16 v[232:233], v188 offset:55360
	ds_read_b64_tr_b16 v[234:235], v190 offset:55360
	ds_read_b64_tr_b16 v[236:237], v186 offset:55296
	ds_read_b64_tr_b16 v[238:239], v187 offset:55296
	v_bitop3_b32 v158, s45, v123, v143 bitop3:0xde
	v_bitop3_b32 v159, s45, v130, v143 bitop3:0xde
	v_mad_u32_u24 v198, v158, s18, 0
	v_mad_u32_u24 v199, v159, s18, 0
	v_add_u32_e32 v191, v198, v125
	v_add_u32_e32 v192, v199, v125
	v_add_u32_e32 v198, v198, v131
	v_add_u32_e32 v199, v199, v131
	ds_read_b64_tr_b16 v[242:243], v192 offset:55296
	ds_read_b64_tr_b16 v[250:251], v192 offset:55328
	ds_read_b64_tr_b16 v[240:241], v191 offset:55296
	ds_read_b64_tr_b16 v[248:249], v191 offset:55328
	ds_read_b64_tr_b16 v[178:179], v191 offset:55360
	ds_read_b64_tr_b16 v[180:181], v192 offset:55360
	ds_read_b64_tr_b16 v[182:183], v198 offset:55296
	ds_read_b64_tr_b16 v[184:185], v199 offset:55296
	s_waitcnt lgkmcnt(15)
	v_mfma_f32_16x16x32_bf16 v[92:95], v[92:95], v[56:59], 0
	v_cmp_gt_u32_e64 s[60:61], s97, v160
	v_cmp_gt_u32_e64 s[62:63], s97, v161
	v_cmp_gt_u32_e64 s[64:65], s97, v162
	v_cmp_gt_u32_e64 s[72:73], s97, v163
	v_mfma_f32_16x16x32_bf16 v[108:111], v[88:91], v[60:63], v[92:95]
	s_cmp_lt_i32 s51, s42
	s_cselect_b32 s101, s97, 0
	s_cselect_b64 s[2:3], -1, 0
	s_cmp_lg_u64 s[2:3], 0
	v_mfma_f32_16x16x32_bf16 v[84:87], v[84:87], v[56:59], 0
	s_addc_u32 s44, s51, 0
	v_mov_b32_e32 v154, v96
	v_cmp_gt_u32_e64 s[74:75], s97, v164
	v_cmp_gt_u32_e64 s[92:93], s97, v165
	v_cmp_gt_u32_e64 s[94:95], s97, v166
	v_cmp_gt_u32_e64 s[98:99], s97, v167
	s_lshl_b32 s52, s44, 5
	s_lshr_b32 s45, s51, 2
	v_pk_mul_f32 v[108:109], v[108:109], v[126:127] op_sel_hi:[1,0]
	v_pk_mul_f32 v[110:111], v[110:111], v[126:127] op_sel_hi:[1,0]
	v_pk_fma_f32 v[108:109], v[160:161], v[128:129], v[108:109] op_sel:[0,1,0] op_sel_hi:[1,1,1] neg_lo:[0,1,0] neg_hi:[0,1,0]
	v_pk_fma_f32 v[110:111], v[162:163], v[128:129], v[110:111] op_sel:[0,1,0] op_sel_hi:[1,1,1] neg_lo:[0,1,0] neg_hi:[0,1,0]
	v_mfma_f32_16x16x32_bf16 v[104:107], v[80:83], v[60:63], v[84:87]
	v_cndmask_b32_e64 v108, v144, v108, s[60:61]
	v_cndmask_b32_e64 v109, v144, v109, s[62:63]
	v_cndmask_b32_e64 v110, v144, v110, s[64:65]
	v_cndmask_b32_e64 v111, v144, v111, s[72:73]
	v_mfma_f32_16x16x32_bf16 v[76:79], v[76:79], v[56:59], 0
	v_max3_f32 v157, v108, s30, v109
	v_max3_f32 v157, v157, v110, v111
	v_pk_add_f32 v[160:161], v[160:161], v[176:177] op_sel_hi:[1,0]
	v_pk_add_f32 v[162:163], v[162:163], v[176:177] op_sel_hi:[1,0]
	v_cmp_gt_u32_e64 s[60:61], s101, v168
	v_cmp_gt_u32_e64 s[62:63], s101, v169
	v_cmp_gt_u32_e64 s[64:65], s101, v170
	v_cmp_gt_u32_e64 s[72:73], s101, v171
	s_xor_b32 s45, s45, s17
	s_lshl_b32 s45, s45, 7
	v_pk_mul_f32 v[104:105], v[104:105], v[126:127] op_sel_hi:[1,0]
	v_pk_mul_f32 v[106:107], v[106:107], v[126:127] op_sel_hi:[1,0]
	v_pk_fma_f32 v[104:105], v[164:165], v[128:129], v[104:105] op_sel:[0,1,0] op_sel_hi:[1,1,1] neg_lo:[0,1,0] neg_hi:[0,1,0]
	v_pk_fma_f32 v[106:107], v[166:167], v[128:129], v[106:107] op_sel:[0,1,0] op_sel_hi:[1,1,1] neg_lo:[0,1,0] neg_hi:[0,1,0]
	v_mfma_f32_16x16x32_bf16 v[100:103], v[72:75], v[60:63], v[76:79]
	v_cndmask_b32_e64 v104, v144, v104, s[74:75]
	v_cndmask_b32_e64 v105, v144, v105, s[92:93]
	v_cndmask_b32_e64 v106, v144, v106, s[94:95]
	v_cndmask_b32_e64 v107, v144, v107, s[98:99]
	v_mfma_f32_16x16x32_bf16 v[68:71], v[68:71], v[56:59], 0
	v_max3_f32 v157, v157, v104, v105
	v_max3_f32 v157, v157, v106, v107
	v_pk_add_f32 v[164:165], v[164:165], v[176:177] op_sel_hi:[1,0]
	v_pk_add_f32 v[166:167], v[166:167], v[176:177] op_sel_hi:[1,0]
	v_cmp_gt_u32_e64 s[74:75], s101, v172
	v_cmp_gt_u32_e64 s[92:93], s101, v173
	v_cmp_gt_u32_e64 s[94:95], s101, v174
	v_cmp_gt_u32_e64 s[98:99], s101, v175
	s_and_b32 s45, s45, 0x80
	s_and_b32 s50, s43, 0x60
	v_pk_mul_f32 v[100:101], v[100:101], v[126:127] op_sel_hi:[1,0]
	v_pk_mul_f32 v[102:103], v[102:103], v[126:127] op_sel_hi:[1,0]
	v_pk_fma_f32 v[100:101], v[168:169], v[128:129], v[100:101] op_sel:[0,1,0] op_sel_hi:[1,1,1] neg_lo:[0,1,0] neg_hi:[0,1,0]
	v_pk_fma_f32 v[102:103], v[170:171], v[128:129], v[102:103] op_sel:[0,1,0] op_sel_hi:[1,1,1] neg_lo:[0,1,0] neg_hi:[0,1,0]
	v_mfma_f32_16x16x32_bf16 v[200:203], v[64:67], v[60:63], v[68:71]
	v_cndmask_b32_e64 v100, v144, v100, s[60:61]
	v_cndmask_b32_e64 v101, v144, v101, s[62:63]
	v_cndmask_b32_e64 v102, v144, v102, s[64:65]
	v_cndmask_b32_e64 v103, v144, v103, s[72:73]
	v_max3_f32 v157, v157, v100, v101
	v_max3_f32 v157, v157, v102, v103
	v_pk_add_f32 v[168:169], v[168:169], v[176:177] op_sel_hi:[1,0]
	v_pk_add_f32 v[170:171], v[170:171], v[176:177] op_sel_hi:[1,0]
	s_or_b32 s45, s45, s50
	s_lshr_b32 s50, s44, 2
	s_xor_b32 s50, s50, s17
	s_nop 1
	v_pk_mul_f32 v[200:201], v[200:201], v[126:127] op_sel_hi:[1,0]
	v_pk_mul_f32 v[202:203], v[202:203], v[126:127] op_sel_hi:[1,0]
	v_pk_fma_f32 v[200:201], v[172:173], v[128:129], v[200:201] op_sel:[0,1,0] op_sel_hi:[1,1,1] neg_lo:[0,1,0] neg_hi:[0,1,0]
	v_pk_fma_f32 v[202:203], v[174:175], v[128:129], v[202:203] op_sel:[0,1,0] op_sel_hi:[1,1,1] neg_lo:[0,1,0] neg_hi:[0,1,0]
	v_cndmask_b32_e64 v200, v144, v200, s[74:75]
	v_cndmask_b32_e64 v201, v144, v201, s[92:93]
	v_cndmask_b32_e64 v202, v144, v202, s[94:95]
	v_cndmask_b32_e64 v203, v144, v203, s[98:99]
	v_max3_f32 v157, v157, v200, v201
	v_max3_f32 v157, v157, v202, v203
	v_pk_add_f32 v[172:173], v[172:173], v[176:177] op_sel_hi:[1,0]
	v_pk_add_f32 v[174:175], v[174:175], v[176:177] op_sel_hi:[1,0]
	ds_bpermute_b32 v156, v150, v157
	s_lshl_b32 s50, s50, 7
	s_and_b32 s50, s50, 0x80
	s_and_b32 s44, s52, 0x60
	s_or_b32 s44, s50, s44
	s_waitcnt lgkmcnt(0)
	v_max_f32_e32 v156, v156, v156
	v_max_f32_e32 v157, v157, v156
	ds_bpermute_b32 v156, v151, v157
	s_add_i32 s50, s51, 2
	s_min_i32 s44, s50, s42
	s_add_i32 s45, s51, 3
	s_lshr_b32 s51, s44, 2
	s_xor_b32 s51, s51, s17
	s_waitcnt lgkmcnt(0)
	v_max3_f32 v96, v154, v157, v156
	v_sub_f32_e32 v155, v154, v96
	v_pk_add_f32 v[108:109], v[108:109], v[96:97] op_sel_hi:[1,0] neg_lo:[0,1] neg_hi:[0,1]
	v_pk_add_f32 v[110:111], v[110:111], v[96:97] op_sel_hi:[1,0] neg_lo:[0,1] neg_hi:[0,1]
	v_exp_f32_e32 v154, v155
	v_pk_add_f32 v[104:105], v[104:105], v[96:97] op_sel_hi:[1,0] neg_lo:[0,1] neg_hi:[0,1]
	v_exp_f32_e32 v108, v108
	v_pk_add_f32 v[106:107], v[106:107], v[96:97] op_sel_hi:[1,0] neg_lo:[0,1] neg_hi:[0,1]
	v_exp_f32_e32 v109, v109
	v_pk_mul_f32 v[54:55], v[54:55], v[154:155] op_sel_hi:[1,0]
	v_exp_f32_e32 v110, v110
	v_pk_mul_f32 v[52:53], v[52:53], v[154:155] op_sel_hi:[1,0]
	v_exp_f32_e32 v111, v111
	v_pk_mul_f32 v[50:51], v[50:51], v[154:155] op_sel_hi:[1,0]
	v_exp_f32_e32 v104, v104
	v_pk_mul_f32 v[48:49], v[48:49], v[154:155] op_sel_hi:[1,0]
	v_exp_f32_e32 v105, v105
	v_pk_mul_f32 v[46:47], v[46:47], v[154:155] op_sel_hi:[1,0]
	v_exp_f32_e32 v106, v106
	v_pk_mul_f32 v[44:45], v[44:45], v[154:155] op_sel_hi:[1,0]
	v_exp_f32_e32 v107, v107
	v_pk_mul_f32 v[42:43], v[42:43], v[154:155] op_sel_hi:[1,0]
	v_pk_mul_f32 v[40:41], v[40:41], v[154:155] op_sel_hi:[1,0]
	v_cvt_pk_bf16_f32 v212, v108, v109
	v_cvt_pk_bf16_f32 v213, v110, v111
	v_cvt_pk_bf16_f32 v214, v104, v105
	v_cvt_pk_bf16_f32 v215, v106, v107
	v_pk_add_f32 v[100:101], v[100:101], v[96:97] op_sel_hi:[1,0] neg_lo:[0,1] neg_hi:[0,1]
	v_pk_add_f32 v[102:103], v[102:103], v[96:97] op_sel_hi:[1,0] neg_lo:[0,1] neg_hi:[0,1]
	v_pk_add_f32 v[200:201], v[200:201], v[96:97] op_sel_hi:[1,0] neg_lo:[0,1] neg_hi:[0,1]
	v_pk_add_f32 v[202:203], v[202:203], v[96:97] op_sel_hi:[1,0] neg_lo:[0,1] neg_hi:[0,1]
	s_lshl_b32 s51, s51, 7
	s_lshl_b32 s44, s44, 5
	v_mfma_f32_16x16x32_bf16 v[52:55], v[224:227], v[212:215], v[52:55]
	v_exp_f32_e32 v100, v100
	v_exp_f32_e32 v101, v101
	s_min_i32 s45, s45, s42
	s_and_b32 s51, s51, 0x80
	s_and_b32 s44, s44, 0x60
	v_mfma_f32_16x16x32_bf16 v[48:51], v[228:231], v[212:215], v[48:51]
	v_exp_f32_e32 v102, v102
	v_exp_f32_e32 v103, v103
	s_or_b32 s44, s51, s44
	s_lshr_b32 s51, s45, 2
	v_mfma_f32_16x16x32_bf16 v[44:47], v[232:235], v[212:215], v[44:47]
	v_exp_f32_e32 v200, v200
	v_pk_add_f32 v[204:205], v[108:109], v[110:111]
	v_exp_f32_e32 v201, v201
	s_xor_b32 s51, s51, s17
	v_mfma_f32_16x16x32_bf16 v[40:43], v[236:239], v[212:215], v[40:43]
	v_exp_f32_e32 v202, v202
	v_pk_add_f32 v[206:207], v[104:105], v[106:107]
	v_exp_f32_e32 v203, v203
	v_cvt_pk_bf16_f32 v216, v100, v101
	v_cvt_pk_bf16_f32 v217, v102, v103
	v_cvt_pk_bf16_f32 v218, v200, v201
	v_cvt_pk_bf16_f32 v219, v202, v203
	v_pk_add_f32 v[210:211], v[100:101], v[102:103]
	v_pk_add_f32 v[156:157], v[200:201], v[202:203]
	s_lshl_b32 s51, s51, 7
	s_lshl_b32 s45, s45, 5
	v_pk_add_f32 v[204:205], v[204:205], v[206:207]
	v_mfma_f32_16x16x32_bf16 v[52:55], v[240:243], v[216:219], v[52:55]
	v_pk_add_f32 v[210:211], v[210:211], v[156:157]
	s_and_b32 s51, s51, 0x80
	s_and_b32 s45, s45, 0x60
	v_mfma_f32_16x16x32_bf16 v[48:51], v[248:251], v[216:219], v[48:51]
	v_pk_add_f32 v[204:205], v[204:205], v[210:211]
	s_or_b32 s45, s51, s45
	s_add_i32 s43, s43, 64
	v_mfma_f32_16x16x32_bf16 v[44:47], v[178:181], v[216:219], v[44:47]
	v_add_f32_e32 v204, v204, v205
	v_subrev_u32_e32 v152, 64, v152
	s_cmp_gt_i32 s50, s42
	v_mfma_f32_16x16x32_bf16 v[40:43], v[182:185], v[216:219], v[40:43]
	v_fma_f32 v97, v97, v154, v204
	s_mov_b32 s51, s50
	s_cbranch_scc0 .LBB0_413
	s_mov_b64 s[2:3], 0
